# low-rank K-slice + LayerNorm loops: 16 per-row parameter vectors requested together ahead of the next-row prefetch, one counted wait instead of eight vmcnt(0)
# speedup vs baseline: 1.0074x; 1.0059x over previous
.LBB0_1623:
	s_or_b64 exec, exec, s[12:13]
	s_waitcnt vmcnt(5)
	v_mov_b32_e32 v46, v39
	v_mov_b32_e32 v47, v21
	v_mov_b32_e32 v39, v20
	v_pk_mul_f32 v[20:21], v[46:47], v[42:43] op_sel_hi:[1,0]
	s_add_i32 s11, s6, 0xffffc000
	s_lshr_b32 s11, s11, 12
	s_ashr_i32 s10, s6, 13
	s_add_i32 s11, s11, 2
	s_cmpk_lt_i32 s6, 0x4000
	s_cselect_b32 s6, s10, s11
	v_readlane_b32 s8, v255, 11
	s_add_i32 s6, s6, s8
	s_mul_i32 s10, s6, 9
	v_mov_b32_e32 v44, v35
	v_mov_b32_e32 v45, v5
	v_mov_b32_e32 v35, v4
	s_ashr_i32 s11, s10, 31
	v_mov_b32_e32 v4, v41
	v_mov_b32_e32 v5, v23
	s_lshl_b64 s[10:11], s[10:11], 12
	v_pk_mul_f32 v[4:5], v[4:5], v[42:43] op_sel_hi:[1,0]
	s_movk_i32 s6, 0x7000
	v_mov_b32_e32 v41, v22
	v_pk_mul_f32 v[22:23], v[40:41], v[42:43] op_sel_hi:[1,0]
	v_pk_mul_f32 v[44:45], v[44:45], v[42:43] op_sel_hi:[1,0]
	v_readlane_b32 s8, v254, 12
	v_readlane_b32 s9, v254, 13
	v_pk_fma_f32 v[56:57], v[4:5], v[70:71], v[74:75]
	v_lshl_add_u64 v[4:5], v[30:31], 0, s[10:11]
	v_pk_fma_f32 v[58:59], v[20:21], v[68:69], v[72:73]
	v_add_co_u32_e32 v52, vcc, s6, v4
	s_mov_b32 s6, 0x2c00000
	s_nop 0
	v_addc_co_u32_e32 v53, vcc, 0, v5, vcc
	s_mov_b64 s[10:11], 0x6000
	v_lshl_add_u64 v[20:21], v[4:5], 0, s[10:11]
	s_mov_b64 s[10:11], 0x7000
	v_lshl_add_u64 v[4:5], v[4:5], 0, s[10:11]
	v_pk_add_f32 v[52:53], v[80:81], 1.0 op_sel_hi:[1,0]
	s_nop 0
	v_pk_fma_f32 v[46:47], v[58:59], v[52:53], v[76:77]
	v_pk_add_f32 v[54:55], v[82:83], 1.0 op_sel_hi:[1,0]
	v_cvt_pk_bf16_f32 v52, v46, v47
	v_lshl_add_u64 v[46:47], s[92:93], 0, v[32:33]
	v_add_co_u32_e32 v46, vcc, s6, v46
	v_pk_fma_f32 v[48:49], v[56:57], v[54:55], v[78:79]
	s_nop 0
	v_addc_co_u32_e32 v47, vcc, 0, v47, vcc
	v_cvt_pk_bf16_f32 v53, v48, v49
	global_store_dwordx2 v[46:47], v[52:53], off
	v_pk_mul_f32 v[48:49], v[38:39], v[42:43] op_sel_hi:[1,0]
	v_lshl_add_u64 v[32:33], v[32:33], 0, s[8:9]
	v_readlane_b32 s8, v254, 14
	v_readlane_b32 s9, v254, 15
	s_add_u32 s0, s0, s8
	s_addc_u32 s1, s1, s9
	s_andn2_b64 vcc, exec, s[2:3]
	s_mov_b32 s6, s7
	v_pk_fma_f32 v[22:23], v[22:23], v[86:87], v[90:91]
	v_pk_fma_f32 v[48:49], v[48:49], v[84:85], v[88:89]
	v_pk_add_f32 v[52:53], v[96:97], 1.0 op_sel_hi:[1,0]
	v_pk_add_f32 v[54:55], v[98:99], 1.0 op_sel_hi:[1,0]
	v_pk_fma_f32 v[38:39], v[48:49], v[52:53], v[92:93]
	v_pk_fma_f32 v[22:23], v[22:23], v[54:55], v[94:95]
	v_cvt_pk_bf16_f32 v38, v38, v39
	s_nop 0
	v_cvt_pk_bf16_f32 v39, v22, v23
	global_store_dwordx2 v[46:47], v[38:39], off offset:512
	s_nop 0
	v_mov_b32_e32 v22, v37
	v_mov_b32_e32 v23, v7
	v_pk_mul_f32 v[22:23], v[22:23], v[42:43] op_sel_hi:[1,0]
	v_mov_b32_e32 v37, v6
	v_pk_mul_f32 v[6:7], v[36:37], v[42:43] op_sel_hi:[1,0]
	v_pk_fma_f32 v[22:23], v[22:23], v[102:103], v[106:107]
	v_pk_fma_f32 v[44:45], v[44:45], v[100:101], v[104:105]
	v_pk_add_f32 v[52:53], v[112:113], 1.0 op_sel_hi:[1,0]
	v_pk_add_f32 v[48:49], v[114:115], 1.0 op_sel_hi:[1,0]
	v_pk_fma_f32 v[38:39], v[44:45], v[52:53], v[108:109]
	v_pk_fma_f32 v[22:23], v[22:23], v[48:49], v[110:111]
	v_cvt_pk_bf16_f32 v38, v38, v39
	s_nop 0
	v_cvt_pk_bf16_f32 v39, v22, v23
	global_store_dwordx2 v[46:47], v[38:39], off offset:1024
	v_pk_mul_f32 v[22:23], v[34:35], v[42:43] op_sel_hi:[1,0]
	v_pk_fma_f32 v[36:37], v[6:7], v[118:119], v[122:123]
	v_pk_fma_f32 v[34:35], v[22:23], v[116:117], v[120:121]
	s_nop 0
	s_waitcnt vmcnt(4)
	v_mov_b32_e32 v39, v16
	v_mov_b32_e32 v41, v18
	v_mov_b32_e32 v38, v12
	v_mov_b32_e32 v40, v14
	v_pk_add_f32 v[4:5], v[128:129], 1.0 op_sel_hi:[1,0]
	v_pk_add_f32 v[6:7], v[130:131], 1.0 op_sel_hi:[1,0]
	v_pk_fma_f32 v[4:5], v[34:35], v[4:5], v[124:125]
	v_pk_fma_f32 v[6:7], v[36:37], v[6:7], v[126:127]
	v_cvt_pk_bf16_f32 v4, v4, v5
	v_mov_b32_e32 v21, v17
	v_cvt_pk_bf16_f32 v5, v6, v7
	global_store_dwordx2 v[46:47], v[4:5], off offset:1536
	v_mov_b32_e32 v23, v19
	v_mov_b32_e32 v20, v13
	v_mov_b32_e32 v22, v15
	v_mov_b32_e32 v35, v8
	v_mov_b32_e32 v5, v9
	v_mov_b32_e32 v37, v10
	v_mov_b32_e32 v7, v11
	v_mov_b32_e32 v34, v0
	v_mov_b32_e32 v4, v1
	v_mov_b32_e32 v36, v2
	v_mov_b32_e32 v6, v3
	s_cbranch_vccz .LBB0_1626
.LBB0_1624:
	s_add_i32 s7, s6, s82
	s_cmpk_gt_i32 s7, 0x7fff
	s_cselect_b64 s[2:3], -1, 0
	s_cmp_lt_i32 s7, 0x8000
	s_cselect_b32 s10, s7, s6
	s_ashr_i32 s11, s10, 31
	s_lshl_b64 s[10:11], s[10:11], 12
	v_lshl_add_u64 v[0:1], v[24:25], 0, s[10:11]
	s_add_i32 s101, s6, 0xffffc000
	s_lshr_b32 s101, s101, 12
	s_add_i32 s101, s101, 2
	s_ashr_i32 s100, s6, 13
	s_cmpk_lt_i32 s6, 0x4000
	s_cselect_b32 s100, s100, s101
	v_readlane_b32 s101, v255, 11
	s_nop 1
	s_add_i32 s100, s100, s101
	s_mul_i32 s100, s100, 9
	s_ashr_i32 s101, s100, 31
	s_lshl_b64 s[100:101], s[100:101], 12
	v_lshl_add_u64 v[60:61], v[30:31], 0, s[100:101]
	s_mov_b64 s[100:101], 0x6000
	v_lshl_add_u64 v[62:63], v[60:61], 0, s[100:101]
	s_mov_b64 s[100:101], 0x7000
	v_lshl_add_u64 v[64:65], v[60:61], 0, s[100:101]
	global_load_dwordx4 v[68:71], v[26:27], off
	global_load_dwordx4 v[72:75], v[28:29], off
	global_load_dwordx4 v[76:79], v[62:63], off
	global_load_dwordx4 v[80:83], v[64:65], off
	global_load_dwordx4 v[84:87], v[26:27], off offset:1024
	global_load_dwordx4 v[88:91], v[28:29], off offset:1024
	global_load_dwordx4 v[92:95], v[62:63], off offset:1024
	global_load_dwordx4 v[96:99], v[64:65], off offset:1024
	global_load_dwordx4 v[100:103], v[26:27], off offset:2048
	global_load_dwordx4 v[104:107], v[28:29], off offset:2048
	global_load_dwordx4 v[108:111], v[62:63], off offset:2048
	global_load_dwordx4 v[112:115], v[64:65], off offset:2048
	global_load_dwordx4 v[116:119], v[26:27], off offset:3072
	global_load_dwordx4 v[120:123], v[28:29], off offset:3072
	global_load_dwordx4 v[124:127], v[62:63], off offset:3072
	global_load_dwordx4 v[128:131], v[64:65], off offset:3072
	global_load_dwordx4 v[16:19], v[0:1], off
	global_load_dwordx4 v[12:15], v[0:1], off offset:1024
	global_load_dwordx4 v[8:11], v[0:1], off offset:2048
	s_nop 0
	global_load_dwordx4 v[0:3], v[0:1], off offset:3072
	v_pk_add_f32 v[42:43], v[38:39], v[20:21]
	s_mov_b32 s8, 0x800000
	v_pk_add_f32 v[42:43], v[40:41], v[42:43]
	s_nop 0
	v_pk_add_f32 v[42:43], v[22:23], v[42:43]
	s_nop 0
	v_add_f32_e32 v43, 0, v43
	v_add_f32_e32 v44, v42, v43
	v_pk_add_f32 v[42:43], v[34:35], v[4:5]
	s_nop 0
	v_pk_add_f32 v[42:43], v[36:37], v[42:43]
	s_nop 0
	v_pk_add_f32 v[42:43], v[6:7], v[42:43]
	s_nop 0
	v_add_f32_e32 v43, v43, v44
	v_add_f32_e32 v42, v42, v43
	s_nop 1
	v_add_f32_dpp v42, v42, v42 quad_perm:[1,0,3,2] row_mask:0xf bank_mask:0xf bound_ctrl:1
	s_nop 1
	v_add_f32_dpp v42, v42, v42 quad_perm:[2,3,0,1] row_mask:0xf bank_mask:0xf bound_ctrl:1
	s_nop 1
	v_add_f32_dpp v42, v42, v42 row_half_mirror row_mask:0xf bank_mask:0xf bound_ctrl:1
	s_nop 1
	v_add_f32_dpp v42, v42, v42 row_mirror row_mask:0xf bank_mask:0xf bound_ctrl:1
	s_nop 0
	v_readlane_b32 s12, v42, 16
	v_readlane_b32 s13, v42, 48
	v_readlane_b32 s10, v42, 0
	v_readlane_b32 s11, v42, 32
	v_mov_b32_e32 v42, s12
	v_mov_b32_e32 v43, s13
	v_pk_add_f32 v[42:43], s[10:11], v[42:43]
	s_nop 0
	v_add_f32_e32 v43, v42, v43
	v_fmac_f32_e32 v21, 0xba800000, v43
	v_fmac_f32_e32 v20, 0xba800000, v43
	v_fmac_f32_e32 v39, 0xba800000, v43
	v_fmac_f32_e32 v38, 0xba800000, v43
	v_mov_b32_e32 v46, v21
	v_mov_b32_e32 v47, v20
	v_fmac_f32_e32 v41, 0xba800000, v43
	v_fmac_f32_e32 v40, 0xba800000, v43
	v_mov_b32_e32 v44, v39
	v_mov_b32_e32 v45, v38
	v_pk_mul_f32 v[46:47], v[46:47], v[46:47]
	v_fmac_f32_e32 v23, 0xba800000, v43
	v_fmac_f32_e32 v22, 0xba800000, v43
	v_pk_fma_f32 v[44:45], v[44:45], v[44:45], v[46:47]
	v_mov_b32_e32 v46, v41
	v_mov_b32_e32 v47, v40
	v_pk_fma_f32 v[44:45], v[46:47], v[46:47], v[44:45]
	v_mov_b32_e32 v46, v23
	v_mov_b32_e32 v47, v22
	v_fmac_f32_e32 v5, 0xba800000, v43
	v_fmac_f32_e32 v4, 0xba800000, v43
	v_pk_fma_f32 v[44:45], v[46:47], v[46:47], v[44:45]
	v_fmac_f32_e32 v35, 0xba800000, v43
	v_fmac_f32_e32 v34, 0xba800000, v43
	v_pk_mul_f32 v[46:47], v[4:5], v[4:5]
	v_fmac_f32_e32 v37, 0xba800000, v43
	v_fmac_f32_e32 v36, 0xba800000, v43
	v_pk_fma_f32 v[46:47], v[34:35], v[34:35], v[46:47]
	v_fmac_f32_e32 v7, 0xba800000, v43
	v_fmac_f32_e32 v6, 0xba800000, v43
	v_pk_fma_f32 v[46:47], v[36:37], v[36:37], v[46:47]
	v_add_f32_e32 v42, v44, v45
	v_pk_fma_f32 v[46:47], v[6:7], v[6:7], v[46:47]
	s_nop 0
	v_add_f32_e32 v42, v47, v42
	v_add_f32_e32 v42, v46, v42
	s_nop 1
	v_add_f32_dpp v42, v42, v42 quad_perm:[1,0,3,2] row_mask:0xf bank_mask:0xf bound_ctrl:1
	s_nop 1
	v_add_f32_dpp v42, v42, v42 quad_perm:[2,3,0,1] row_mask:0xf bank_mask:0xf bound_ctrl:1
	s_nop 1
	v_add_f32_dpp v42, v42, v42 row_half_mirror row_mask:0xf bank_mask:0xf bound_ctrl:1
	s_nop 1
	v_add_f32_dpp v42, v42, v42 row_mirror row_mask:0xf bank_mask:0xf bound_ctrl:1
	s_nop 0
	v_readlane_b32 s12, v42, 16
	v_readlane_b32 s13, v42, 48
	v_readlane_b32 s10, v42, 0
	v_readlane_b32 s11, v42, 32
	v_mov_b32_e32 v44, s12
	v_mov_b32_e32 v45, s13
	v_pk_add_f32 v[44:45], s[10:11], v[44:45]
	s_nop 0
	v_add_f32_e32 v42, v44, v45
	v_fmamk_f32 v42, v42, 0x3a800000, v232
	v_mul_f32_e32 v44, 0x4b800000, v42
	v_cmp_gt_f32_e32 vcc, s8, v42
	s_nop 1
	v_cndmask_b32_e32 v42, v42, v44, vcc
	v_rsq_f32_e32 v42, v42
	s_nop 0
	v_mul_f32_e32 v44, 0x45800000, v42
	v_cndmask_b32_e32 v42, v42, v44, vcc
	s_and_saveexec_b64 s[12:13], s[38:39]
	s_cbranch_execz .LBB0_1623
	s_add_u32 s10, s92, s0
	v_mul_f32_e32 v44, 0x3a800000, v43
	s_addc_u32 s11, s93, s1
	v_mov_b32_e32 v45, v42
	global_store_dwordx2 v51, v[44:45], s[10:11]
	s_branch .LBB0_1623

.LBB0_1933:
	s_or_b64 exec, exec, s[26:27]
	s_waitcnt vmcnt(5)
	v_mov_b32_e32 v46, v39
	v_mov_b32_e32 v47, v21
	v_mov_b32_e32 v39, v20
	v_pk_mul_f32 v[20:21], v[46:47], v[42:43] op_sel_hi:[1,0]
	s_add_i32 s13, s12, 0xffffc000
	s_lshr_b32 s13, s13, 12
	s_ashr_i32 s11, s12, 13
	s_add_i32 s13, s13, 2
	s_cmpk_lt_i32 s12, 0x4000
	s_cselect_b32 s11, s11, s13
	v_readlane_b32 s8, v255, 11
	s_add_i32 s11, s11, s8
	s_mul_i32 s12, s11, 9
	v_mov_b32_e32 v44, v35
	v_mov_b32_e32 v45, v5
	v_mov_b32_e32 v35, v4
	s_ashr_i32 s13, s12, 31
	v_mov_b32_e32 v4, v41
	v_mov_b32_e32 v5, v23
	s_lshl_b64 s[12:13], s[12:13], 12
	v_pk_mul_f32 v[4:5], v[4:5], v[42:43] op_sel_hi:[1,0]
	s_movk_i32 s8, 0x4000
	v_mov_b32_e32 v41, v22
	v_pk_mul_f32 v[22:23], v[40:41], v[42:43] op_sel_hi:[1,0]
	v_pk_mul_f32 v[44:45], v[44:45], v[42:43] op_sel_hi:[1,0]
	v_pk_fma_f32 v[56:57], v[4:5], v[70:71], v[74:75]
	v_lshl_add_u64 v[4:5], v[30:31], 0, s[12:13]
	v_pk_fma_f32 v[58:59], v[20:21], v[68:69], v[72:73]
	v_add_co_u32_e32 v52, vcc, s8, v4
	s_mov_b32 s8, 0x2c00000
	s_nop 0
	v_addc_co_u32_e32 v53, vcc, 0, v5, vcc
	s_mov_b64 s[12:13], 0x3000
	v_lshl_add_u64 v[20:21], v[4:5], 0, s[12:13]
	s_mov_b64 s[12:13], 0x4000
	v_lshl_add_u64 v[4:5], v[4:5], 0, s[12:13]
	s_mov_b32 s12, s10
	v_pk_add_f32 v[52:53], v[80:81], 1.0 op_sel_hi:[1,0]
	s_nop 0
	v_pk_fma_f32 v[46:47], v[58:59], v[52:53], v[76:77]
	v_pk_add_f32 v[54:55], v[82:83], 1.0 op_sel_hi:[1,0]
	v_cvt_pk_bf16_f32 v52, v46, v47
	v_lshl_add_u64 v[46:47], s[92:93], 0, v[32:33]
	v_add_co_u32_e32 v46, vcc, s8, v46
	v_pk_fma_f32 v[48:49], v[56:57], v[54:55], v[78:79]
	s_nop 0
	v_addc_co_u32_e32 v47, vcc, 0, v47, vcc
	v_cvt_pk_bf16_f32 v53, v48, v49
	global_store_dwordx2 v[46:47], v[52:53], off
	v_pk_mul_f32 v[48:49], v[38:39], v[42:43] op_sel_hi:[1,0]
	v_readlane_b32 s8, v254, 12
	v_readlane_b32 s9, v254, 13
	v_pk_fma_f32 v[22:23], v[22:23], v[86:87], v[90:91]
	v_pk_fma_f32 v[48:49], v[48:49], v[84:85], v[88:89]
	v_lshl_add_u64 v[32:33], v[32:33], 0, s[8:9]
	v_readlane_b32 s8, v254, 14
	v_readlane_b32 s9, v254, 15
	s_add_u32 s0, s0, s8
	s_addc_u32 s1, s1, s9
	s_andn2_b64 vcc, exec, s[6:7]
	v_pk_add_f32 v[52:53], v[96:97], 1.0 op_sel_hi:[1,0]
	v_pk_add_f32 v[54:55], v[98:99], 1.0 op_sel_hi:[1,0]
	v_pk_fma_f32 v[38:39], v[48:49], v[52:53], v[92:93]
	v_pk_fma_f32 v[22:23], v[22:23], v[54:55], v[94:95]
	v_cvt_pk_bf16_f32 v38, v38, v39
	s_nop 0
	v_cvt_pk_bf16_f32 v39, v22, v23
	global_store_dwordx2 v[46:47], v[38:39], off offset:512
	s_nop 0
	v_mov_b32_e32 v22, v37
	v_mov_b32_e32 v23, v7
	v_pk_mul_f32 v[22:23], v[22:23], v[42:43] op_sel_hi:[1,0]
	v_mov_b32_e32 v37, v6
	v_pk_mul_f32 v[6:7], v[36:37], v[42:43] op_sel_hi:[1,0]
	v_pk_fma_f32 v[22:23], v[22:23], v[102:103], v[106:107]
	v_pk_fma_f32 v[44:45], v[44:45], v[100:101], v[104:105]
	v_pk_add_f32 v[52:53], v[112:113], 1.0 op_sel_hi:[1,0]
	v_pk_add_f32 v[48:49], v[114:115], 1.0 op_sel_hi:[1,0]
	v_pk_fma_f32 v[38:39], v[44:45], v[52:53], v[108:109]
	v_pk_fma_f32 v[22:23], v[22:23], v[48:49], v[110:111]
	v_cvt_pk_bf16_f32 v38, v38, v39
	s_nop 0
	v_cvt_pk_bf16_f32 v39, v22, v23
	global_store_dwordx2 v[46:47], v[38:39], off offset:1024
	v_pk_mul_f32 v[22:23], v[34:35], v[42:43] op_sel_hi:[1,0]
	v_pk_fma_f32 v[36:37], v[6:7], v[118:119], v[122:123]
	v_pk_fma_f32 v[34:35], v[22:23], v[116:117], v[120:121]
	s_nop 0
	s_waitcnt vmcnt(4)
	v_mov_b32_e32 v39, v16
	v_mov_b32_e32 v41, v18
	v_mov_b32_e32 v38, v12
	v_mov_b32_e32 v40, v14
	v_pk_add_f32 v[4:5], v[128:129], 1.0 op_sel_hi:[1,0]
	v_pk_add_f32 v[6:7], v[130:131], 1.0 op_sel_hi:[1,0]
	v_pk_fma_f32 v[4:5], v[34:35], v[4:5], v[124:125]
	v_pk_fma_f32 v[6:7], v[36:37], v[6:7], v[126:127]
	v_cvt_pk_bf16_f32 v4, v4, v5
	v_mov_b32_e32 v21, v17
	v_cvt_pk_bf16_f32 v5, v6, v7
	global_store_dwordx2 v[46:47], v[4:5], off offset:1536
	v_mov_b32_e32 v23, v19
	v_mov_b32_e32 v20, v13
	v_mov_b32_e32 v22, v15
	v_mov_b32_e32 v35, v8
	v_mov_b32_e32 v5, v9
	v_mov_b32_e32 v37, v10
	v_mov_b32_e32 v7, v11
	v_mov_b32_e32 v34, v0
	v_mov_b32_e32 v4, v1
	v_mov_b32_e32 v36, v2
	v_mov_b32_e32 v6, v3
	s_cbranch_vccz .LBB0_1982
.LBB0_1934:
	s_add_i32 s10, s12, s82
	s_cmpk_gt_i32 s10, 0x7fff
	s_cselect_b64 s[6:7], -1, 0
	s_cmp_lt_i32 s10, 0x8000
	s_cselect_b32 s14, s10, s12
	s_ashr_i32 s15, s14, 31
	s_lshl_b64 s[14:15], s[14:15], 12
	v_lshl_add_u64 v[0:1], v[24:25], 0, s[14:15]
	s_add_i32 s101, s12, 0xffffc000
	s_lshr_b32 s101, s101, 12
	s_add_i32 s101, s101, 2
	s_ashr_i32 s100, s12, 13
	s_cmpk_lt_i32 s12, 0x4000
	s_cselect_b32 s100, s100, s101
	v_readlane_b32 s101, v255, 11
	s_nop 1
	s_add_i32 s100, s100, s101
	s_mul_i32 s100, s100, 9
	s_ashr_i32 s101, s100, 31
	s_lshl_b64 s[100:101], s[100:101], 12
	v_lshl_add_u64 v[60:61], v[30:31], 0, s[100:101]
	s_mov_b64 s[100:101], 0x3000
	v_lshl_add_u64 v[62:63], v[60:61], 0, s[100:101]
	s_mov_b64 s[100:101], 0x4000
	v_lshl_add_u64 v[64:65], v[60:61], 0, s[100:101]
	global_load_dwordx4 v[68:71], v[26:27], off
	global_load_dwordx4 v[72:75], v[28:29], off
	global_load_dwordx4 v[76:79], v[62:63], off
	global_load_dwordx4 v[80:83], v[64:65], off
	global_load_dwordx4 v[84:87], v[26:27], off offset:1024
	global_load_dwordx4 v[88:91], v[28:29], off offset:1024
	global_load_dwordx4 v[92:95], v[62:63], off offset:1024
	global_load_dwordx4 v[96:99], v[64:65], off offset:1024
	global_load_dwordx4 v[100:103], v[26:27], off offset:2048
	global_load_dwordx4 v[104:107], v[28:29], off offset:2048
	global_load_dwordx4 v[108:111], v[62:63], off offset:2048
	global_load_dwordx4 v[112:115], v[64:65], off offset:2048
	global_load_dwordx4 v[116:119], v[26:27], off offset:3072
	global_load_dwordx4 v[120:123], v[28:29], off offset:3072
	global_load_dwordx4 v[124:127], v[62:63], off offset:3072
	global_load_dwordx4 v[128:131], v[64:65], off offset:3072
	global_load_dwordx4 v[16:19], v[0:1], off
	global_load_dwordx4 v[12:15], v[0:1], off offset:1024
	global_load_dwordx4 v[8:11], v[0:1], off offset:2048
	s_nop 0
	global_load_dwordx4 v[0:3], v[0:1], off offset:3072
	v_pk_add_f32 v[42:43], v[38:39], v[20:21]
	s_mov_b32 s8, 0x800000
	v_pk_add_f32 v[42:43], v[40:41], v[42:43]
	s_nop 0
	v_pk_add_f32 v[42:43], v[22:23], v[42:43]
	s_nop 0
	v_add_f32_e32 v43, 0, v43
	v_add_f32_e32 v44, v42, v43
	v_pk_add_f32 v[42:43], v[34:35], v[4:5]
	s_nop 0
	v_pk_add_f32 v[42:43], v[36:37], v[42:43]
	s_nop 0
	v_pk_add_f32 v[42:43], v[6:7], v[42:43]
	s_nop 0
	v_add_f32_e32 v43, v43, v44
	v_add_f32_e32 v42, v42, v43
	s_nop 1
	v_add_f32_dpp v42, v42, v42 quad_perm:[1,0,3,2] row_mask:0xf bank_mask:0xf bound_ctrl:1
	s_nop 1
	v_add_f32_dpp v42, v42, v42 quad_perm:[2,3,0,1] row_mask:0xf bank_mask:0xf bound_ctrl:1
	s_nop 1
	v_add_f32_dpp v42, v42, v42 row_half_mirror row_mask:0xf bank_mask:0xf bound_ctrl:1
	s_nop 1
	v_add_f32_dpp v42, v42, v42 row_mirror row_mask:0xf bank_mask:0xf bound_ctrl:1
	s_nop 0
	v_readlane_b32 s11, v42, 16
	v_readlane_b32 s13, v42, 48
	v_readlane_b32 s14, v42, 0
	v_readlane_b32 s15, v42, 32
	v_mov_b32_e32 v42, s11
	v_mov_b32_e32 v43, s13
	v_pk_add_f32 v[42:43], s[14:15], v[42:43]
	s_nop 0
	v_add_f32_e32 v43, v42, v43
	v_fmac_f32_e32 v21, 0xba800000, v43
	v_fmac_f32_e32 v20, 0xba800000, v43
	v_fmac_f32_e32 v39, 0xba800000, v43
	v_fmac_f32_e32 v38, 0xba800000, v43
	v_mov_b32_e32 v46, v21
	v_mov_b32_e32 v47, v20
	v_fmac_f32_e32 v41, 0xba800000, v43
	v_fmac_f32_e32 v40, 0xba800000, v43
	v_mov_b32_e32 v44, v39
	v_mov_b32_e32 v45, v38
	v_pk_mul_f32 v[46:47], v[46:47], v[46:47]
	v_fmac_f32_e32 v23, 0xba800000, v43
	v_fmac_f32_e32 v22, 0xba800000, v43
	v_pk_fma_f32 v[44:45], v[44:45], v[44:45], v[46:47]
	v_mov_b32_e32 v46, v41
	v_mov_b32_e32 v47, v40
	v_pk_fma_f32 v[44:45], v[46:47], v[46:47], v[44:45]
	v_mov_b32_e32 v46, v23
	v_mov_b32_e32 v47, v22
	v_fmac_f32_e32 v5, 0xba800000, v43
	v_fmac_f32_e32 v4, 0xba800000, v43
	v_pk_fma_f32 v[44:45], v[46:47], v[46:47], v[44:45]
	v_fmac_f32_e32 v35, 0xba800000, v43
	v_fmac_f32_e32 v34, 0xba800000, v43
	v_pk_mul_f32 v[46:47], v[4:5], v[4:5]
	v_fmac_f32_e32 v37, 0xba800000, v43
	v_fmac_f32_e32 v36, 0xba800000, v43
	v_pk_fma_f32 v[46:47], v[34:35], v[34:35], v[46:47]
	v_fmac_f32_e32 v7, 0xba800000, v43
	v_fmac_f32_e32 v6, 0xba800000, v43
	v_pk_fma_f32 v[46:47], v[36:37], v[36:37], v[46:47]
	v_add_f32_e32 v42, v44, v45
	v_pk_fma_f32 v[46:47], v[6:7], v[6:7], v[46:47]
	s_nop 0
	v_add_f32_e32 v42, v47, v42
	v_add_f32_e32 v42, v46, v42
	s_nop 1
	v_add_f32_dpp v42, v42, v42 quad_perm:[1,0,3,2] row_mask:0xf bank_mask:0xf bound_ctrl:1
	s_nop 1
	v_add_f32_dpp v42, v42, v42 quad_perm:[2,3,0,1] row_mask:0xf bank_mask:0xf bound_ctrl:1
	s_nop 1
	v_add_f32_dpp v42, v42, v42 row_half_mirror row_mask:0xf bank_mask:0xf bound_ctrl:1
	s_nop 1
	v_add_f32_dpp v42, v42, v42 row_mirror row_mask:0xf bank_mask:0xf bound_ctrl:1
	s_nop 0
	v_readlane_b32 s11, v42, 16
	v_readlane_b32 s13, v42, 48
	v_readlane_b32 s14, v42, 0
	v_readlane_b32 s15, v42, 32
	v_mov_b32_e32 v44, s11
	v_mov_b32_e32 v45, s13
	v_pk_add_f32 v[44:45], s[14:15], v[44:45]
	s_nop 0
	v_add_f32_e32 v42, v44, v45
	v_fmamk_f32 v42, v42, 0x3a800000, v232
	v_mul_f32_e32 v44, 0x4b800000, v42
	v_cmp_gt_f32_e32 vcc, s8, v42
	s_nop 1
	v_cndmask_b32_e32 v42, v42, v44, vcc
	v_rsq_f32_e32 v42, v42
	s_nop 0
	v_mul_f32_e32 v44, 0x45800000, v42
	v_cndmask_b32_e32 v42, v42, v44, vcc
	s_and_saveexec_b64 s[26:27], s[38:39]
	s_cbranch_execz .LBB0_1933
	s_add_u32 s14, s92, s0
	v_mul_f32_e32 v44, 0x3a800000, v43
	s_addc_u32 s15, s93, s1
	v_mov_b32_e32 v45, v42
	global_store_dwordx2 v51, v[44:45], s[14:15]
	s_branch .LBB0_1933
